# 6.3 rule 1: one static s_setprio 1 for waves 4-7 at kernel entry, GEMM-loop flips deleted
# baseline (speedup 1.0000x reference)
; #define LAS __attribute__((address_space(3)))
; __device__ __forceinline__ unsigned xb_ld(unsigned* p)              { return __hip_atomic_load(p, __ATOMIC_RELAXED, __HIP_MEMORY_SCOPE_AGENT); }
; __device__ __forceinline__ unsigned xb_add(unsigned* p, unsigned v) { return __hip_atomic_fetch_add(p, v, __ATOMIC_RELAXED, __HIP_MEMORY_SCOPE_AGENT); }
; __global__ void __launch_bounds__(512, 2) mega_fwd(Args args) {
;     extern __shared__ __attribute__((aligned(16))) unsigned char lds_raw[];
;     LAS unsigned char* lds = (LAS unsigned char*)lds_raw;
;     const int tid = threadIdx.x, lane = tid & 63, wave = __builtin_amdgcn_readfirstlane(tid >> 6);
;     const int G = gridDim.x, cu = blockIdx.x;
;     const int gw = cu * 8 + wave, NGW = G * 8;
;     unsigned char* ws = args.ws;
;     const float* x = args.in[0]; const float* mem = args.in[1]; const int* positions = (const int*)args.in[2];
;     float* out = args.out;
;     bf16_t* WGU = (bf16_t*)(ws + WS_WGU); bf16_t* WD = (bf16_t*)(ws + WS_WD); bf16_t* WIN = (bf16_t*)(ws + WS_WIN); bf16_t* WOUT = (bf16_t*)(ws + WS_WOUT);
;     bf16_t* WMKV = (bf16_t*)(ws + WS_WMKV); bf16_t* WMQ = (bf16_t*)(ws + WS_WMQ); bf16_t* WMO = (bf16_t*)(ws + WS_WMO); bf16_t* WQUP = (bf16_t*)(ws + WS_WQUP); bf16_t* WKVUP = (bf16_t*)(ws + WS_WKVUP);
;     bf16_t* H = (bf16_t*)(ws + WS_H); bf16_t* CAT = H; bf16_t* ACT = (bf16_t*)(ws + WS_ACT);
;     bf16_t* Z = (bf16_t*)(ws + WS_Z); bf16_t* GVT = (bf16_t*)(ws + WS_GVT); bf16_t* QA = (bf16_t*)(ws + WS_QA); bf16_t* KVA = (bf16_t*)(ws + WS_KVA);
;     bf16_t* KDT = (bf16_t*)(ws + WS_KDT); float* DEC = (float*)(ws + WS_DEC); bf16_t* MK = (bf16_t*)(ws + WS_MK); bf16_t* MVT = (bf16_t*)(ws + WS_MVT);
;     bf16_t* Qb = (bf16_t*)(ws + WS_Q); bf16_t* Kb = (bf16_t*)(ws + WS_K); bf16_t* VT = (bf16_t*)(ws + WS_VT); bf16_t* MEMN = (bf16_t*)(ws + WS_MEMN);
;     bf16_t* MQ = (bf16_t*)(ws + WS_MQ); bf16_t* OMEM = (bf16_t*)(ws + WS_OMEM); bf16_t* OG = (bf16_t*)(ws + WS_OG);
;     LAS float* scr = (LAS float*)(lds + wave * 16384);
;     const int lo = args.ph_lo, hi = args.ph_hi;
;     ...
;     unsigned* const gbar = (unsigned*)(ws + WS_BAR); unsigned epoch = 0;
;     volatile LAS unsigned* xst = (volatile LAS unsigned*)(lds + 132608);
;     if (tid < 4) xst[tid] = 0u;
;     __syncthreads();
;     const XcdBarrier xbar = xcd_barrier_post(gbar, xst);
_Z8mega_fwd4Args:
	s_load_dwordx2 s[86:87], s[0:1], 0x100
	s_load_dword s15, s[0:1], 0x118
	s_mov_b32 s80, s2
	s_add_u32 s2, s0, 0x118
	v_and_b32_e32 v185, 0x3ff, v0
	s_addc_u32 s3, s1, 0
	v_readfirstlane_b32 s10, v185
	v_writelane_b32 v238, s2, 0
	v_cmp_gt_u32_e32 vcc, 4, v185
	s_nop 0
	v_writelane_b32 v238, s3, 1
	s_lshr_b32 s94, s10, 6
	s_cmp_ge_u32 s94, 4
	s_cbranch_scc0 .Lprio_done
	s_setprio 1
.Lprio_done:
	s_and_saveexec_b64 s[2:3], vcc
	v_lshl_add_u32 v1, v185, 2, 0
	v_add_u32_e32 v1, 0x20600, v1
	v_mov_b32_e32 v2, 0
	ds_write_b32 v1, v2
	s_or_b64 exec, exec, s[2:3]
	s_load_dwordx2 s[92:93], s[0:1], 0x108
	s_load_dword s6, s[0:1], 0x114
	s_waitcnt lgkmcnt(0)
	s_add_u32 s88, s86, 0x6700000
	s_barrier
	s_getreg_b32 s2, hwreg(HW_REG_XCC_ID, 0, 4)
	s_addc_u32 s89, s87, 0
	s_and_b32 s2, s2, 15
	v_writelane_b32 v238, s2, 2
	v_cmp_eq_u32_e64 s[4:5], 0, v185
	s_mov_b64 s[2:3], exec
	s_nop 0
	v_writelane_b32 v238, s4, 3
	s_nop 1
	v_writelane_b32 v238, s5, 4
	s_and_b64 s[4:5], s[2:3], s[4:5]
	s_mov_b64 exec, s[4:5]
	s_cbranch_execz .LBB0_5
	s_mov_b64 s[4:5], exec
	v_mbcnt_lo_u32_b32 v1, s4, 0
	v_mbcnt_hi_u32_b32 v1, s5, v1
	v_cmp_eq_u32_e32 vcc, 0, v1
	s_and_b64 s[8:9], exec, vcc
	s_mov_b64 exec, s[8:9]
	s_cbranch_execz .LBB0_5
	v_readlane_b32 s7, v238, 2
	s_lshl_b32 s7, s7, 8
	s_bcnt1_i32_b64 s4, s[4:5]
	v_mov_b32_e32 v1, s7
	v_mov_b32_e32 v2, s4
	global_atomic_add v1, v2, s[88:89] offset:1024
